# attention: all eight K and V loads of the next key tile issued behind the current tile's QK^T MFMAs / V staging (software prefetch, V back into its own registers); skipped tiles never fetched
# baseline (speedup 1.0000x reference)
.LBB0_625:
	s_ashr_i32 s18, s38, 12
	s_bfe_u32 s4, s38, 0x20007
	s_and_b32 s39, s38, 0x7f
	s_cmp_eq_u32 s18, 1
	s_cselect_b32 s2, 4, 16
	s_cselect_b32 s3, 2, 4
	s_cmpk_lt_u32 s38, 0x1000
	s_cselect_b32 s46, 1, s2
	s_cselect_b32 s19, 0, s3
	s_lshl_b32 s2, s18, 2
	s_or_b32 s47, s2, s4
	s_add_i32 s2, s47, 1
	v_cvt_f32_i32_e32 v0, s2
	s_xor_b32 s2, s19, 7
	s_lshr_b32 s49, s39, s2
	s_lshr_b32 s48, 0x80, s19
	v_mul_f32_e32 v0, 0xc1000000, v0
	v_div_scale_f32 v2, s[2:3], s15, s15, v0
	v_rcp_f32_e32 v3, v2
	s_add_i32 s48, s48, -1
	s_and_b32 s2, s48, s39
	s_lshl_b32 s39, s2, 5
	v_fma_f32 v4, -v2, v3, 1.0
	v_fmac_f32_e32 v3, v4, v3
	v_div_scale_f32 v4, vcc, v0, s15, v0
	v_mul_f32_e32 v5, v4, v3
	v_fma_f32 v6, -v2, v5, v4
	v_fmac_f32_e32 v5, v6, v3
	v_fma_f32 v2, -v2, v5, v4
	v_div_fmas_f32 v2, v2, v3, v5
	v_div_fixup_f32 v0, v2, s15, v0
	v_cmp_gt_f32_e32 vcc, s17, v0
	s_and_b64 s[2:3], vcc, exec
	s_cselect_b32 s48, 0xffffffc0, 0
	s_lshl_b32 s2, s38, 3
	s_and_b32 s2, s2, 0x7000
	v_or_b32_e32 v2, s39, v118
	s_or_b32 s49, s49, s2
	v_lshlrev_b32_e32 v2, s19, v2
	v_add_u32_e32 v92, s49, v2
	v_mad_u64_u32 v[2:3], s[2:3], v92, s20, v[82:83]
	s_lshl_b32 s2, s47, 6
	s_ashr_i32 s3, s2, 31
	s_lshl_b64 s[2:3], s[2:3], 1
	v_lshl_add_u64 v[94:95], v[2:3], 0, s[2:3]
	v_lshl_add_u64 v[2:3], v[94:95], 0, v[84:85]
	global_load_dwordx4 v[50:53], v[2:3], off
	global_load_dwordx4 v[54:57], v[2:3], off offset:32
	global_load_dwordx4 v[58:61], v[2:3], off offset:64
	global_load_dwordx4 v[62:65], v[2:3], off offset:96
	v_cndmask_b32_e32 v4, 0, v122, vcc
	v_add_f32_e32 v0, v0, v4
	v_exp_f32_e32 v0, v0
	s_mulk_i32 s49, 0x1200
	v_cvt_f32_ubyte0_e32 v2, s46
	s_add_u32 s46, s30, s49
	v_ldexp_f32 v0, v0, s48
	v_mul_f32_e32 v0, v0, v2
	s_addc_u32 s47, s31, 0
	v_mov_b32_e32 v14, v1
	v_mov_b32_e32 v15, v1
	v_mul_f32_e32 v97, 0x3fb8aa3b, v0
	s_add_u32 s2, s46, s2
	v_mov_b32_e32 v0, v1
	v_mov_b32_e32 v2, v1
	v_mov_b32_e32 v3, v1
	v_mov_b32_e32 v4, v1
	v_mov_b32_e32 v5, v1
	v_mov_b32_e32 v6, v1
	v_mov_b32_e32 v7, v1
	v_mov_b32_e32 v8, v1
	v_mov_b32_e32 v9, v1
	v_mov_b32_e32 v10, v1
	v_mov_b32_e32 v11, v1
	v_mov_b32_e32 v12, v1
	v_mov_b32_e32 v13, v1
	v_mov_b64_e32 v[32:33], v[14:15]
	s_addc_u32 s3, s47, s3
	v_mov_b64_e32 v[30:31], v[12:13]
	v_mov_b64_e32 v[28:29], v[10:11]
	v_mov_b64_e32 v[26:27], v[8:9]
	v_mov_b64_e32 v[24:25], v[6:7]
	v_mov_b64_e32 v[22:23], v[4:5]
	v_mov_b64_e32 v[20:21], v[2:3]
	v_mov_b64_e32 v[18:19], v[0:1]
	v_mov_b64_e32 v[16:17], v[14:15]
	v_mov_b32_e32 v93, v1
	v_lshl_add_u64 v[98:99], s[2:3], 0, v[86:87]
	v_lshl_add_u64 v[100:101], s[2:3], 0, v[84:85]
	v_mov_b32_e32 v102, v97
	v_mov_b32_e32 v103, v97
	v_or_b32_e32 v89, s39, v119
	v_add_u32_e32 v131, s39, v121
	v_mov_b32_e32 v133, 0xf149f2ca
	v_mov_b32_e32 v130, v1
	v_mov_b64_e32 v[14:15], v[12:13]
	v_mov_b64_e32 v[12:13], v[10:11]
	v_mov_b64_e32 v[10:11], v[8:9]
	v_mov_b64_e32 v[8:9], v[6:7]
	v_mov_b64_e32 v[6:7], v[4:5]
	v_mov_b64_e32 v[4:5], v[2:3]
	v_mov_b64_e32 v[2:3], v[0:1]
	s_lshr_b32 s54, s39, 5
	s_mul_i32 s55, s54, 0xcd
	s_lshr_b32 s55, s55, 10
	s_mul_i32 s55, s55, 5
	s_sub_i32 s54, s54, s55
	s_sub_i32 s54, 4, s54
	s_lshl_b32 s46, s54, 5
	v_subrev_u32_e32 v132, s46, v120
	s_mov_b32 s56, 5
	s_mov_b32 s98, s46
	s_add_i32 s99, s39, s98
	s_addk_i32 s99, 0xff80
	s_cmp_lt_i32 s99, 0
	s_cbranch_scc1 .Lmy_kpf_p
	v_add_u32_e32 v228, s98, v131
	v_mov_b32_e32 v229, 0
	v_lshlrev_b64 v[230:231], s19, v[228:229]
	v_mad_u64_u32 v[232:233], s[100:101], v230, s20, v[100:101]
	v_mad_u32_u24 v233, v231, s20, v233
	global_load_dwordx4 v[212:215], v[232:233], off offset:1536
	global_load_dwordx4 v[216:219], v[232:233], off offset:1568
	global_load_dwordx4 v[220:223], v[232:233], off offset:1600
	global_load_dwordx4 v[224:227], v[232:233], off offset:1632
	v_add_u32_e32 v228, s98, v89
	v_mov_b32_e32 v235, 0
	v_add_u32_e32 v234, 0xffffff80, v228
	v_lshlrev_b64 v[236:237], s19, v[234:235]
	v_mad_u64_u32 v[238:239], s[100:101], v236, s20, v[98:99]
	v_mad_u32_u24 v239, v237, s20, v239
	global_load_dwordx4 v[146:149], v[238:239], off offset:3072
	v_add_u32_e32 v234, 0xffffff88, v228
	v_lshlrev_b64 v[236:237], s19, v[234:235]
	v_mad_u64_u32 v[238:239], s[100:101], v236, s20, v[98:99]
	v_mad_u32_u24 v239, v237, s20, v239
	global_load_dwordx4 v[186:189], v[238:239], off offset:3072
	v_add_u32_e32 v234, 0xffffff90, v228
	v_lshlrev_b64 v[236:237], s19, v[234:235]
	v_mad_u64_u32 v[238:239], s[100:101], v236, s20, v[98:99]
	v_mad_u32_u24 v239, v237, s20, v239
	global_load_dwordx4 v[190:193], v[238:239], off offset:3072
	v_add_u32_e32 v234, 0xffffff98, v228
	v_lshlrev_b64 v[236:237], s19, v[234:235]
	v_mad_u64_u32 v[238:239], s[100:101], v236, s20, v[98:99]
	v_mad_u32_u24 v239, v237, s20, v239
	global_load_dwordx4 v[194:197], v[238:239], off offset:3072

.Lmy_kpf_skip:
	s_cmp_eq_u32 s56, 1
	s_cbranch_scc1 .Lmy_kpf_s
	s_add_i32 s98, s46, 32
	s_cmpk_lg_i32 s98, 0xa0
	s_cselect_b32 s98, s98, 0
	s_add_i32 s99, s39, s98
	s_addk_i32 s99, 0xff80
	s_cmp_lt_i32 s99, 0
	s_cbranch_scc1 .Lmy_kpf_s
	v_add_u32_e32 v228, s98, v131
	v_mov_b32_e32 v229, 0
	v_lshlrev_b64 v[230:231], s19, v[228:229]
	v_mad_u64_u32 v[232:233], s[100:101], v230, s20, v[100:101]
	v_mad_u32_u24 v233, v231, s20, v233
	global_load_dwordx4 v[212:215], v[232:233], off offset:1536
	global_load_dwordx4 v[216:219], v[232:233], off offset:1568
	global_load_dwordx4 v[220:223], v[232:233], off offset:1600
	global_load_dwordx4 v[224:227], v[232:233], off offset:1632
	v_add_u32_e32 v228, s98, v89
	v_mov_b32_e32 v235, 0
	v_add_u32_e32 v234, 0xffffff80, v228
	v_lshlrev_b64 v[236:237], s19, v[234:235]
	v_mad_u64_u32 v[238:239], s[100:101], v236, s20, v[98:99]
	v_mad_u32_u24 v239, v237, s20, v239
	global_load_dwordx4 v[146:149], v[238:239], off offset:3072
	v_add_u32_e32 v234, 0xffffff88, v228
	v_lshlrev_b64 v[236:237], s19, v[234:235]
	v_mad_u64_u32 v[238:239], s[100:101], v236, s20, v[98:99]
	v_mad_u32_u24 v239, v237, s20, v239
	global_load_dwordx4 v[186:189], v[238:239], off offset:3072
	v_add_u32_e32 v234, 0xffffff90, v228
	v_lshlrev_b64 v[236:237], s19, v[234:235]
	v_mad_u64_u32 v[238:239], s[100:101], v236, s20, v[98:99]
	v_mad_u32_u24 v239, v237, s20, v239
	global_load_dwordx4 v[190:193], v[238:239], off offset:3072
	v_add_u32_e32 v234, 0xffffff98, v228
	v_lshlrev_b64 v[236:237], s19, v[234:235]
	v_mad_u64_u32 v[238:239], s[100:101], v236, s20, v[98:99]
	v_mad_u32_u24 v239, v237, s20, v239
	global_load_dwordx4 v[194:197], v[238:239], off offset:3072

.LBB0_627:
	s_add_i32 s2, s39, s46
	s_addk_i32 s2, 0xff80
	s_cmp_lt_i32 s2, 0
	s_cbranch_scc1 .Lmy_kpf_skip
	v_and_b32_e32 v38, 64, v125
	v_add_u32_e32 v96, 64, v38
	v_add_u32_e32 v175, v132, v67
	v_add_u32_e32 v176, v132, v66
	v_cvt_f32_i32_e32 v157, v175
	v_cvt_f32_i32_e32 v156, v176
	v_add_u32_e32 v177, v69, v132
	v_add_u32_e32 v178, v68, v132
	v_cvt_f32_i32_e32 v159, v177
	v_cvt_f32_i32_e32 v158, v178
	v_xor_b32_e32 v0, 32, v125
	v_add_u32_e32 v168, v74, v132
	v_add_u32_e32 v179, v71, v132
	v_add_u32_e32 v180, v70, v132
	v_cvt_f32_i32_e32 v91, v168
	v_cvt_f32_i32_e32 v161, v179
	v_cvt_f32_i32_e32 v160, v180
	v_cmp_lt_i32_e32 vcc, v0, v96
	v_pk_mul_f32 v[156:157], v[102:103], v[156:157]
	v_pk_mul_f32 v[158:159], v[102:103], v[158:159]
	v_cndmask_b32_e32 v0, v125, v0, vcc
	v_cmp_gt_u32_e32 vcc, s21, v175
	v_lshlrev_b32_e32 v184, 2, v0
	v_add_u32_e32 v163, v75, v132
	v_pk_mul_f32 v[160:161], v[102:103], v[160:161]
	v_mov_b32_e32 v155, v97
	v_add_u32_e32 v170, v76, v132
	v_mov_b32_e32 v117, v97
	v_add_u32_e32 v169, v77, v132
	v_mov_b32_e32 v113, v97
	v_add_u32_e32 v172, v78, v132
	v_mov_b32_e32 v111, v97
	v_add_u32_e32 v174, v80, v132
	v_mov_b32_e32 v109, v97
	v_add_u32_e32 v171, v79, v132
	v_mov_b32_e32 v107, v97
	v_add_u32_e32 v173, v81, v132
	v_mov_b32_e32 v105, v97
	v_add_u32_e32 v182, v73, v132
	v_add_u32_e32 v183, v72, v132
	v_cvt_f32_i32_e32 v165, v182
	v_cvt_f32_i32_e32 v164, v183
	s_waitcnt vmcnt(7)
	v_mfma_f32_32x32x16_bf16 v[34:49], v[212:215], v[50:53], 0
	s_waitcnt vmcnt(6)
	v_mfma_f32_32x32x16_bf16 v[34:49], v[216:219], v[54:57], v[34:49]
	s_waitcnt vmcnt(5)
	v_mfma_f32_32x32x16_bf16 v[34:49], v[220:223], v[58:61], v[34:49]
	s_waitcnt vmcnt(3)
	ds_write_b128 v123, v[146:149]
	s_waitcnt vmcnt(2)
	ds_write_b128 v123, v[186:189] offset:1024
	s_waitcnt vmcnt(1)
	ds_write_b128 v123, v[190:193] offset:2048
	s_waitcnt vmcnt(0)
	ds_write_b128 v123, v[194:197] offset:3072
	v_mfma_f32_32x32x16_bf16 v[34:49], v[224:227], v[62:65], v[34:49]
	s_waitcnt lgkmcnt(0)
	s_cmp_eq_u32 s56, 1
	s_cbranch_scc1 .Lmy_kpf_b
	s_add_i32 s98, s46, 32
	s_cmpk_lg_i32 s98, 0xa0
	s_cselect_b32 s98, s98, 0
	s_add_i32 s99, s39, s98
	s_addk_i32 s99, 0xff80
	s_cmp_lt_i32 s99, 0
	s_cbranch_scc1 .Lmy_kpf_b
	v_add_u32_e32 v228, s98, v131
	v_mov_b32_e32 v229, 0
	v_lshlrev_b64 v[230:231], s19, v[228:229]
	v_mad_u64_u32 v[232:233], s[100:101], v230, s20, v[100:101]
	v_mad_u32_u24 v233, v231, s20, v233
	global_load_dwordx4 v[212:215], v[232:233], off offset:1536
	global_load_dwordx4 v[216:219], v[232:233], off offset:1568
	global_load_dwordx4 v[220:223], v[232:233], off offset:1600
	global_load_dwordx4 v[224:227], v[232:233], off offset:1632
	v_add_u32_e32 v228, s98, v89
	v_mov_b32_e32 v235, 0
	v_add_u32_e32 v234, 0xffffff80, v228
	v_lshlrev_b64 v[236:237], s19, v[234:235]
	v_mad_u64_u32 v[238:239], s[100:101], v236, s20, v[98:99]
	v_mad_u32_u24 v239, v237, s20, v239
	global_load_dwordx4 v[146:149], v[238:239], off offset:3072
	v_add_u32_e32 v234, 0xffffff88, v228
	v_lshlrev_b64 v[236:237], s19, v[234:235]
	v_mad_u64_u32 v[238:239], s[100:101], v236, s20, v[98:99]
	v_mad_u32_u24 v239, v237, s20, v239
	global_load_dwordx4 v[186:189], v[238:239], off offset:3072
	v_add_u32_e32 v234, 0xffffff90, v228
	v_lshlrev_b64 v[236:237], s19, v[234:235]
	v_mad_u64_u32 v[238:239], s[100:101], v236, s20, v[98:99]
	v_mad_u32_u24 v239, v237, s20, v239
	global_load_dwordx4 v[190:193], v[238:239], off offset:3072
	v_add_u32_e32 v234, 0xffffff98, v228
	v_lshlrev_b64 v[236:237], s19, v[234:235]
	v_mad_u64_u32 v[238:239], s[100:101], v236, s20, v[98:99]
	v_mad_u32_u24 v239, v237, s20, v239
	global_load_dwordx4 v[194:197], v[238:239], off offset:3072
